# attention deferred-max loop: QK K-fragment reads pipelined through 7 rotating buffers, S accumulated in place
# speedup vs baseline: 1.0133x; 1.0007x over previous
; #define LAS __attribute__((address_space(3)))
; #pragma unroll
;     for (int sub = 0; sub < 4; ++sub) { s[0][sub] = (f32x4){init0, init0, init0, init0}; s[1][sub] = (f32x4){init1, init1, init1, init1}; }
; #pragma unroll
;     for (int kc = 0; kc < 4; ++kc) {
;         bf16x8 kf[4];
; #pragma unroll
;         for (int sub = 0; sub < 4; ++sub) kf[sub] = *(const LAS bf16x8*)(buf + (16 * sub + ql) * KT_PITCH + kc * 64 + g * 16);
; #pragma unroll
;         for (int sub = 0; sub < 4; ++sub) {
;             s[0][sub] = __builtin_amdgcn_mfma_f32_16x16x32_bf16(kf[sub], qf[0][kc], s[0][sub], 0, 0, 0);
;             s[1][sub] = __builtin_amdgcn_mfma_f32_16x16x32_bf16(kf[sub], qf[1][kc], s[1][sub], 0, 0, 0);
;         }
;         if (kc & 1) asm volatile("" ::: "memory");
;     }
; }
; template <int MODE, bool DEFER> ...
;     ...
;     if (DEFER) qk_tile2(s, qf, buf, ql, g, take[0] ? -mrun[0] : -__builtin_inff(), take[1] ? -mrun[1] : -__builtin_inff());
;     else qk_tile2(s, qf, buf, ql, g);
;     if (tile < tile_hi) stage_load<true, true>(R, Kg, VTg, vpitch, (tile + 1) * 64, tid);
;     u32x4 pk[2][2];
;     if (DEFER) {
;         float m0 = local_max16(s[0]), m1 = local_max16(s[1]);
;         if (__any(m0 > DEFER_THRESH || m1 > DEFER_THRESH)) {
.LBB0_1008:
	s_bitcmp1_b32 s1, 0
	s_cselect_b32 s7, 0x8c00, 0
	s_add_i32 s11, s7, 0
	s_lshl_b64 s[12:13], 1, s1
	s_ashr_i32 s7, s6, 31
	v_add_u32_e32 v44, s6, v152
	v_ashrrev_i32_e32 v45, 31, v44
	v_lshlrev_b64 v[44:45], 8, v[44:45]
	v_lshl_add_u64 v[44:45], v[176:177], 0, v[44:45]
	global_load_dwordx4 v[44:47], v[44:45], off
	v_lshl_add_u64 v[48:49], s[6:7], 1, v[178:179]
	v_add_u32_e32 v36, s6, v150
	v_ashrrev_i32_e32 v37, 31, v36
	v_lshlrev_b64 v[36:37], 8, v[36:37]
	v_lshl_add_u64 v[36:37], v[176:177], 0, v[36:37]
	global_load_dwordx4 v[36:39], v[36:37], off
	v_lshl_add_u64 v[40:41], v[48:49], 0, v[164:165]
	v_lshl_add_u64 v[48:49], v[48:49], 0, v[166:167]
	global_load_dwordx4 v[40:43], v[40:41], off
	global_load_dwordx4 v[48:51], v[48:49], off
	v_add3_u32 v3, s11, v149, v201
	ds_read_b128 v[180:183], v3
	ds_read_b128 v[184:187], v3 offset:4352
	ds_read_b128 v[188:191], v3 offset:8704
	ds_read_b128 v[196:199], v3 offset:13056
	ds_read_b128 v[212:215], v3 offset:64
	v_and_b32_e32 v245, s13, v175
	v_and_b32_e32 v244, s12, v174
	v_and_b32_e32 v247, s13, v173
	v_and_b32_e32 v246, s12, v172
	v_cmp_ne_u64_e32 vcc, 0, v[244:245]
	s_nop 0
	s_nop 0
	v_cndmask_b32_e64 v244, v235, -v170, vcc
	v_cmp_ne_u64_e32 vcc, 0, v[246:247]
	v_mov_b32_e32 v245, v244
	v_mov_b32_e32 v246, v244
	v_cndmask_b32_e64 v248, v235, -v171, vcc
	v_mov_b32_e32 v247, v244
	v_mov_b32_e32 v249, v248
	v_mov_b32_e32 v250, v248
	v_mov_b32_e32 v251, v248
	s_waitcnt lgkmcnt(4)
	v_mfma_f32_16x16x32_bf16 v[144:147], v[180:183], v[4:7], v[244:247]
	v_mfma_f32_16x16x32_bf16 v[128:131], v[180:183], v[20:23], v[248:251]
	ds_read_b128 v[180:183], v3 offset:4416
	s_waitcnt lgkmcnt(4)
	v_mfma_f32_16x16x32_bf16 v[140:143], v[184:187], v[4:7], v[244:247]
	v_mfma_f32_16x16x32_bf16 v[124:127], v[184:187], v[20:23], v[248:251]
	ds_read_b128 v[184:187], v3 offset:8768
	s_waitcnt lgkmcnt(4)
	v_mfma_f32_16x16x32_bf16 v[136:139], v[188:191], v[4:7], v[244:247]
	v_mfma_f32_16x16x32_bf16 v[120:123], v[188:191], v[20:23], v[248:251]
	ds_read_b128 v[188:191], v3 offset:13120
	s_waitcnt lgkmcnt(4)
	v_mfma_f32_16x16x32_bf16 v[132:135], v[196:199], v[4:7], v[244:247]
	v_mfma_f32_16x16x32_bf16 v[116:119], v[196:199], v[20:23], v[248:251]
	ds_read_b128 v[196:199], v3 offset:128
	ds_read_b128 v[244:247], v3 offset:4480
	ds_read_b128 v[248:251], v3 offset:8832
	s_waitcnt lgkmcnt(6)
	v_mfma_f32_16x16x32_bf16 v[144:147], v[212:215], v[8:11], v[144:147]
	v_mfma_f32_16x16x32_bf16 v[128:131], v[212:215], v[24:27], v[128:131]
	ds_read_b128 v[212:215], v3 offset:13184
	s_waitcnt lgkmcnt(6)
	v_mfma_f32_16x16x32_bf16 v[140:143], v[180:183], v[8:11], v[140:143]
	v_mfma_f32_16x16x32_bf16 v[124:127], v[180:183], v[24:27], v[124:127]
	ds_read_b128 v[180:183], v3 offset:192
	s_waitcnt lgkmcnt(6)
	v_mfma_f32_16x16x32_bf16 v[136:139], v[184:187], v[8:11], v[136:139]
	v_mfma_f32_16x16x32_bf16 v[120:123], v[184:187], v[24:27], v[120:123]
	ds_read_b128 v[184:187], v3 offset:4544
	s_waitcnt lgkmcnt(6)
	v_mfma_f32_16x16x32_bf16 v[132:135], v[188:191], v[8:11], v[132:135]
	v_mfma_f32_16x16x32_bf16 v[116:119], v[188:191], v[24:27], v[116:119]
	ds_read_b128 v[188:191], v3 offset:8896
	s_waitcnt lgkmcnt(6)
	v_mfma_f32_16x16x32_bf16 v[144:147], v[196:199], v[12:15], v[144:147]
	v_mfma_f32_16x16x32_bf16 v[128:131], v[196:199], v[28:31], v[128:131]
	ds_read_b128 v[196:199], v3 offset:13248
	s_waitcnt lgkmcnt(6)
	v_mfma_f32_16x16x32_bf16 v[140:143], v[244:247], v[12:15], v[140:143]
	v_mfma_f32_16x16x32_bf16 v[124:127], v[244:247], v[28:31], v[124:127]
	s_waitcnt lgkmcnt(5)
	v_mfma_f32_16x16x32_bf16 v[136:139], v[248:251], v[12:15], v[136:139]
	v_mfma_f32_16x16x32_bf16 v[120:123], v[248:251], v[28:31], v[120:123]
	s_waitcnt lgkmcnt(4)
	v_mfma_f32_16x16x32_bf16 v[132:135], v[212:215], v[12:15], v[132:135]
	v_mfma_f32_16x16x32_bf16 v[116:119], v[212:215], v[28:31], v[116:119]
	s_waitcnt lgkmcnt(3)
	v_mfma_f32_16x16x32_bf16 v[144:147], v[180:183], v[16:19], v[144:147]
	v_mfma_f32_16x16x32_bf16 v[128:131], v[180:183], v[32:35], v[128:131]
	s_waitcnt lgkmcnt(2)
	v_mfma_f32_16x16x32_bf16 v[140:143], v[184:187], v[16:19], v[140:143]
	v_mfma_f32_16x16x32_bf16 v[124:127], v[184:187], v[32:35], v[124:127]
	s_waitcnt lgkmcnt(1)
	v_mfma_f32_16x16x32_bf16 v[136:139], v[188:191], v[16:19], v[136:139]
	v_mfma_f32_16x16x32_bf16 v[120:123], v[188:191], v[32:35], v[120:123]
	s_waitcnt lgkmcnt(0)
	v_mfma_f32_16x16x32_bf16 v[132:135], v[196:199], v[16:19], v[132:135]
	v_mfma_f32_16x16x32_bf16 v[116:119], v[196:199], v[32:35], v[116:119]
	v_max3_f32 v3, v144, v144, v145
	v_max3_f32 v3, v3, v146, v147
	v_max3_f32 v151, v128, v128, v129
	v_max3_f32 v151, v151, v130, v131
	v_max3_f32 v3, v3, v140, v141
	v_max3_f32 v151, v151, v124, v125
	v_max3_f32 v3, v3, v142, v143
	v_max3_f32 v151, v151, v126, v127
	v_max3_f32 v3, v3, v136, v137
	v_max3_f32 v151, v151, v120, v121
	v_max3_f32 v3, v3, v138, v139
	v_max3_f32 v151, v151, v122, v123
	v_max3_f32 v3, v3, v132, v133
	v_max3_f32 v151, v151, v116, v117
	v_max3_f32 v3, v3, v134, v135
	v_max3_f32 v151, v151, v118, v119
	v_max_f32_e32 v157, v3, v3
	v_max_f32_e32 v153, v151, v151
	v_max_f32_e32 v153, v157, v153
	v_cmp_lt_f32_e32 vcc, s94, v153
	s_cbranch_vccz .LBB0_1007
; template <int MODE, bool DEFER> ...
;     ...
;             m0 = fmaxf(qmax(m0), 0.f); m1 = fmaxf(qmax(m1), 0.f);
;             const float a0 = __builtin_amdgcn_exp2f(-m0), a1 = __builtin_amdgcn_exp2f(-m1);
;             mrun[0] += m0; mrun[1] += m1; lsum[0] *= a0; lsum[1] *= a1;
; #pragma unroll
;             for (int dt = 0; dt < 8; ++dt) { o[0][dt] = o[0][dt] * a0; o[1][dt] = o[1][dt] * a1; }
; #pragma unroll
;             for (int sub = 0; sub < 4; ++sub) { s[0][sub] = s[0][sub] - m0; s[1][sub] = s[1][sub] - m1; }
	v_mov_b32_e32 v153, v3
	s_nop 1
	v_permlane32_swap_b32_e32 v3, v153
	v_max_f32_e32 v153, v153, v153
	v_max_f32_e32 v3, v3, v3
	v_max_f32_e32 v3, v3, v153
	v_mov_b32_e32 v153, v3
	s_nop 1
	v_permlane16_swap_b32_e32 v3, v153
	v_max3_f32 v180, v3, v153, 0
	v_mov_b32_e32 v3, v151
	s_nop 1
	v_permlane32_swap_b32_e32 v151, v3
	v_max_f32_e32 v3, v3, v3
	v_max_f32_e32 v151, v151, v151
	v_max_f32_e32 v3, v151, v3
	v_mov_b32_e32 v151, v3
	s_nop 1
	v_permlane16_swap_b32_e32 v3, v151
	v_max3_f32 v181, v3, v151, 0
	v_exp_f32_e64 v183, -v180
	v_exp_f32_e64 v182, -v181
	v_pk_add_f32 v[170:171], v[170:171], v[180:181]
	v_sub_f32_e32 v144, v144, v180
	v_mov_b32_e32 v184, v183
	v_pk_mul_f32 v[168:169], v[168:169], v[182:183]
	v_pk_mul_f32 v[106:107], v[106:107], v[184:185] op_sel_hi:[1,0]
	v_pk_mul_f32 v[104:105], v[104:105], v[184:185] op_sel_hi:[1,0]
	v_pk_mul_f32 v[82:83], v[82:83], v[182:183] op_sel_hi:[1,0]
	v_pk_mul_f32 v[80:81], v[80:81], v[182:183] op_sel_hi:[1,0]
	v_pk_mul_f32 v[110:111], v[110:111], v[184:185] op_sel_hi:[1,0]
	v_pk_mul_f32 v[108:109], v[108:109], v[184:185] op_sel_hi:[1,0]
	v_pk_mul_f32 v[78:79], v[78:79], v[182:183] op_sel_hi:[1,0]
	v_pk_mul_f32 v[76:77], v[76:77], v[182:183] op_sel_hi:[1,0]
	v_pk_mul_f32 v[102:103], v[102:103], v[184:185] op_sel_hi:[1,0]
	v_pk_mul_f32 v[100:101], v[100:101], v[184:185] op_sel_hi:[1,0]
	v_pk_mul_f32 v[74:75], v[74:75], v[182:183] op_sel_hi:[1,0]
	v_pk_mul_f32 v[72:73], v[72:73], v[182:183] op_sel_hi:[1,0]
	v_pk_mul_f32 v[98:99], v[98:99], v[184:185] op_sel_hi:[1,0]
	v_pk_mul_f32 v[96:97], v[96:97], v[184:185] op_sel_hi:[1,0]
	v_pk_mul_f32 v[70:71], v[70:71], v[182:183] op_sel_hi:[1,0]
	v_pk_mul_f32 v[68:69], v[68:69], v[182:183] op_sel_hi:[1,0]
	v_pk_mul_f32 v[90:91], v[90:91], v[184:185] op_sel_hi:[1,0]
	v_pk_mul_f32 v[88:89], v[88:89], v[184:185] op_sel_hi:[1,0]
	v_pk_mul_f32 v[62:63], v[62:63], v[182:183] op_sel_hi:[1,0]
	v_pk_mul_f32 v[60:61], v[60:61], v[182:183] op_sel_hi:[1,0]
	v_pk_mul_f32 v[86:87], v[86:87], v[184:185] op_sel_hi:[1,0]
	v_pk_mul_f32 v[84:85], v[84:85], v[184:185] op_sel_hi:[1,0]
	v_pk_mul_f32 v[54:55], v[54:55], v[182:183] op_sel_hi:[1,0]
	v_pk_mul_f32 v[52:53], v[52:53], v[182:183] op_sel_hi:[1,0]
	v_pk_mul_f32 v[94:95], v[94:95], v[184:185] op_sel_hi:[1,0]
	v_pk_mul_f32 v[92:93], v[92:93], v[184:185] op_sel_hi:[1,0]
	v_pk_mul_f32 v[66:67], v[66:67], v[182:183] op_sel_hi:[1,0]
	v_pk_mul_f32 v[64:65], v[64:65], v[182:183] op_sel_hi:[1,0]
	v_pk_mul_f32 v[114:115], v[114:115], v[184:185] op_sel_hi:[1,0]
	v_pk_mul_f32 v[112:113], v[112:113], v[184:185] op_sel_hi:[1,0]
	v_pk_mul_f32 v[58:59], v[58:59], v[182:183] op_sel_hi:[1,0]
	v_pk_mul_f32 v[56:57], v[56:57], v[182:183] op_sel_hi:[1,0]
	v_sub_f32_e32 v145, v145, v180
	v_sub_f32_e32 v146, v146, v180
	v_sub_f32_e32 v147, v147, v180
	v_sub_f32_e32 v128, v128, v181
	v_sub_f32_e32 v129, v129, v181
	v_sub_f32_e32 v130, v130, v181
	v_sub_f32_e32 v131, v131, v181
	v_sub_f32_e32 v140, v140, v180
	v_sub_f32_e32 v141, v141, v180
	v_sub_f32_e32 v142, v142, v180
	v_sub_f32_e32 v143, v143, v180
	v_sub_f32_e32 v124, v124, v181
	v_sub_f32_e32 v125, v125, v181
	v_sub_f32_e32 v126, v126, v181
	v_sub_f32_e32 v127, v127, v181
	v_sub_f32_e32 v136, v136, v180
	v_sub_f32_e32 v137, v137, v180
	v_sub_f32_e32 v138, v138, v180
	v_sub_f32_e32 v139, v139, v180
	v_sub_f32_e32 v120, v120, v181
	v_sub_f32_e32 v121, v121, v181
	v_sub_f32_e32 v122, v122, v181
	v_sub_f32_e32 v123, v123, v181
	v_sub_f32_e32 v132, v132, v180
	v_sub_f32_e32 v133, v133, v180
	v_sub_f32_e32 v134, v134, v180
	v_sub_f32_e32 v135, v135, v180
	v_sub_f32_e32 v116, v116, v181
	v_sub_f32_e32 v117, v117, v181
	v_sub_f32_e32 v118, v118, v181
	v_sub_f32_e32 v119, v119, v181
	s_branch .LBB0_1007
